# tight polling: s_sleep removed from the quad/XCD/neighbour barrier spin loops (poll placement)
# baseline (speedup 1.0000x reference)
.Lp1_spin:
	flat_load_dword v8, v[2:3] sc1
	flat_load_dword v9, v[4:5] sc1
	flat_load_dword v10, v[6:7] sc1
	s_waitcnt vmcnt(0) lgkmcnt(0)
	v_min3_u32 v8, v8, v9, v10
	v_cmp_lt_u32_e32 vcc, v8, v11
	s_cbranch_vccz .Lp1_done
	s_add_i32 s4, s4, 1
	s_cmp_lt_u32 s4, 0x100000
	s_cbranch_scc1 .Lp1_spin

.Lxl_spin_P2:
	flat_load_dword v5, v[2:3] sc1
	s_waitcnt vmcnt(0) lgkmcnt(0)
	v_cmp_lt_u32_e32 vcc, v5, v4
	s_cbranch_vccz .Lxl_done_P2
	s_add_i32 s8, s8, 1
	s_cmp_lt_u32 s8, 0x100000
	s_cbranch_scc1 .Lxl_spin_P2

.Lxl_spin_P4:
	flat_load_dword v5, v[2:3] sc1
	flat_load_dword v10, v[6:7] sc1
	s_waitcnt vmcnt(0) lgkmcnt(0)
	v_cmp_lt_u32_e32 vcc, v5, v4
	v_cmp_lt_u32_e64 s[14:15], v10, v9
	s_or_b64 vcc, vcc, s[14:15]
	s_cbranch_vccz .Lxl_done_P4
	s_add_i32 s8, s8, 1
	s_cmp_lt_u32 s8, 0x100000
	s_cbranch_scc1 .Lxl_spin_P4
